# NSA selected-branch output accumulate: 16 serialized load-wait-store round trips replaced by 16 up-front loads + counted vmcnt(15) waits
# speedup vs baseline: 1.0002x; 1.0002x over previous
.LBB0_609:
	v_mov_b32_e32 v4, v165
	v_readlane_b32 s4, v247, 45
	v_add_u32_e32 v4, s80, v4
	v_ashrrev_i32_e32 v5, 31, v4
	v_lshlrev_b64 v[6:7], 12, v[4:5]
	v_readlane_b32 s5, v247, 46
	v_lshlrev_b64 v[4:5], 10, v[4:5]
	s_mov_b32 s3, s71
	v_lshl_add_u64 v[6:7], s[4:5], 0, v[6:7]
	v_readlane_b32 s4, v247, 31
	v_readlane_b32 s5, v247, 32
	ds_bpermute_b32 v2, v172, v179
	s_mov_b32 s75, s71
	v_lshl_add_u64 v[4:5], s[4:5], 0, v[4:5]
	v_lshl_add_u64 v[4:5], v[4:5], 0, s[2:3]
	global_load_dword v4, v[4:5], off offset:192
	s_waitcnt lgkmcnt(0)
	v_add_f32_e32 v2, v179, v2
	v_lshl_add_u64 v[6:7], v[6:7], 0, s[74:75]
	s_lshl_b32 s3, s84, 1
	s_mov_b32 m0, s85
	v_lshlrev_b32_e32 v100, 1, v164
	v_mov_b32_e32 v101, v3
	v_readlane_b32 s64, v247, 41
	v_mov_b32_e32 v17, 0
	v_mov_b32_e32 v16, 0
	v_mov_b32_e32 v15, 0
	v_mov_b32_e32 v14, 0
	v_mov_b32_e32 v13, 0
	v_mov_b32_e32 v12, 0
	v_mov_b32_e32 v106, 0
	v_readlane_b32 s84, v246, 4
	v_readlane_b32 s86, v246, 6
	v_readlane_b32 s65, v247, 42
	s_movk_i32 s14, 0xe0
	s_mov_b64 s[16:17], 0x1a0000
	v_readlane_b32 s15, v246, 19
	v_readlane_b32 s18, v246, 18
	v_readlane_b32 s85, v246, 5
	v_readlane_b32 s87, v246, 7
	s_waitcnt vmcnt(0)
	v_mul_f32_e32 v4, 0xbfb8aa3b, v4
	v_exp_f32_e32 v4, v4
	s_nop 0
	v_add_f32_e32 v4, 1.0, v4
	v_rcp_f32_e32 v4, v4
	s_nop 0
	v_div_scale_f32 v5, s[4:5], v2, v2, v4
	v_rcp_f32_e32 v8, v5
	v_readlane_b32 s4, v247, 53
	s_add_u32 s3, s4, s3
	v_readlane_b32 s4, v247, 54
	v_fma_f32 v9, -v5, v8, 1.0
	v_fmac_f32_e32 v8, v9, v8
	v_div_scale_f32 v9, vcc, v4, v2, v4
	v_mul_f32_e32 v10, v9, v8
	v_fma_f32 v11, -v5, v10, v9
	v_fmac_f32_e32 v10, v11, v8
	v_fma_f32 v5, -v5, v10, v9
	v_div_fmas_f32 v5, v5, v8, v10
	v_div_fixup_f32 v2, v5, v2, v4
	v_lshl_add_u64 v[4:5], v[148:149], 1, v[6:7]
	global_load_dwordx2 v[192:193], v[4:5], off
	global_load_dwordx2 v[194:195], v[4:5], off offset:16
	global_load_dwordx2 v[196:197], v[4:5], off offset:32
	global_load_dwordx2 v[198:199], v[4:5], off offset:48
	global_load_dwordx2 v[200:201], v[4:5], off offset:64
	global_load_dwordx2 v[202:203], v[4:5], off offset:80
	global_load_dwordx2 v[204:205], v[4:5], off offset:96
	global_load_dwordx2 v[206:207], v[4:5], off offset:112
	global_load_dwordx2 v[208:209], v[4:5], off offset:128
	global_load_dwordx2 v[210:211], v[4:5], off offset:144
	global_load_dwordx2 v[212:213], v[4:5], off offset:160
	global_load_dwordx2 v[214:215], v[4:5], off offset:176
	global_load_dwordx2 v[216:217], v[4:5], off offset:192
	global_load_dwordx2 v[218:219], v[4:5], off offset:208
	global_load_dwordx2 v[220:221], v[4:5], off offset:224
	global_load_dwordx2 v[222:223], v[4:5], off offset:240
	s_addc_u32 s8, s4, 0
	s_add_i32 s9, s73, -8
	s_cmp_gt_i32 s73, 7
	s_cselect_b32 s10, s9, 0
	s_mul_i32 s12, s10, 0x1a0000
	s_mul_hi_i32 s11, s10, 0x1a0000
	s_add_u32 s0, s0, s12
	s_addc_u32 s1, s1, s11
	s_add_u32 s6, s0, 0x1000
	s_addc_u32 s7, s1, 0
	s_lshl_b32 s0, s10, 6
	s_ashr_i32 s1, s0, 31
	s_lshl_b64 s[4:5], s[0:1], 1
	s_add_u32 s4, s3, s4
	s_addc_u32 s5, s8, s5
	s_cmp_le_i32 s10, s73
	v_mov_b32_e32 v11, 0
	v_mov_b32_e32 v10, 0
	s_waitcnt vmcnt(15)
	v_lshlrev_b32_e32 v8, 16, v192
	v_and_b32_e32 v9, 0xffff0000, v192
	v_pk_fma_f32 v[8:9], v[66:67], v[2:3], v[8:9] op_sel_hi:[1,0,1]
	v_mov_b32_e32 v67, 0
	v_cvt_pk_bf16_f32 v6, v8, v9
	v_lshlrev_b32_e32 v8, 16, v193
	v_and_b32_e32 v9, 0xffff0000, v193
	v_pk_fma_f32 v[8:9], v[68:69], v[2:3], v[8:9] op_sel_hi:[1,0,1]
	v_mov_b32_e32 v66, 0
	v_cvt_pk_bf16_f32 v7, v8, v9
	global_store_dwordx2 v[4:5], v[6:7], off
	s_waitcnt vmcnt(15)
	v_lshlrev_b32_e32 v8, 16, v194
	v_and_b32_e32 v9, 0xffff0000, v194
	v_pk_fma_f32 v[8:9], v[70:71], v[2:3], v[8:9] op_sel_hi:[1,0,1]
	s_nop 0
	v_cvt_pk_bf16_f32 v6, v8, v9
	v_lshlrev_b32_e32 v8, 16, v195
	v_and_b32_e32 v9, 0xffff0000, v195
	v_pk_fma_f32 v[8:9], v[72:73], v[2:3], v[8:9] op_sel_hi:[1,0,1]
	s_nop 0
	v_cvt_pk_bf16_f32 v7, v8, v9
	global_store_dwordx2 v[4:5], v[6:7], off offset:16
	s_waitcnt vmcnt(15)
	v_lshlrev_b32_e32 v8, 16, v196
	v_and_b32_e32 v9, 0xffff0000, v196
	v_pk_fma_f32 v[8:9], v[74:75], v[2:3], v[8:9] op_sel_hi:[1,0,1]
	s_nop 0
	v_cvt_pk_bf16_f32 v6, v8, v9
	v_lshlrev_b32_e32 v8, 16, v197
	v_and_b32_e32 v9, 0xffff0000, v197
	v_pk_fma_f32 v[8:9], v[76:77], v[2:3], v[8:9] op_sel_hi:[1,0,1]
	s_nop 0
	v_cvt_pk_bf16_f32 v7, v8, v9
	global_store_dwordx2 v[4:5], v[6:7], off offset:32
	s_waitcnt vmcnt(15)
	v_lshlrev_b32_e32 v8, 16, v198
	v_and_b32_e32 v9, 0xffff0000, v198
	v_pk_fma_f32 v[8:9], v[78:79], v[2:3], v[8:9] op_sel_hi:[1,0,1]
	s_nop 0
	v_cvt_pk_bf16_f32 v6, v8, v9
	v_lshlrev_b32_e32 v8, 16, v199
	v_and_b32_e32 v9, 0xffff0000, v199
	v_pk_fma_f32 v[8:9], v[80:81], v[2:3], v[8:9] op_sel_hi:[1,0,1]
	s_nop 0
	v_cvt_pk_bf16_f32 v7, v8, v9
	global_store_dwordx2 v[4:5], v[6:7], off offset:48
	s_waitcnt vmcnt(15)
	v_lshlrev_b32_e32 v8, 16, v200
	v_and_b32_e32 v9, 0xffff0000, v200
	v_pk_fma_f32 v[8:9], v[50:51], v[2:3], v[8:9] op_sel_hi:[1,0,1]
	v_mov_b32_e32 v51, 0
	v_cvt_pk_bf16_f32 v6, v8, v9
	v_lshlrev_b32_e32 v8, 16, v201
	v_and_b32_e32 v9, 0xffff0000, v201
	v_pk_fma_f32 v[8:9], v[52:53], v[2:3], v[8:9] op_sel_hi:[1,0,1]
	v_mov_b32_e32 v53, 0
	v_cvt_pk_bf16_f32 v7, v8, v9
	global_store_dwordx2 v[4:5], v[6:7], off offset:64
	v_mov_b32_e32 v52, 0
	v_mov_b32_e32 v50, 0
	s_waitcnt vmcnt(15)
	v_lshlrev_b32_e32 v8, 16, v202
	v_and_b32_e32 v9, 0xffff0000, v202
	v_pk_fma_f32 v[8:9], v[54:55], v[2:3], v[8:9] op_sel_hi:[1,0,1]
	v_mov_b32_e32 v55, 0
	v_cvt_pk_bf16_f32 v6, v8, v9
	v_lshlrev_b32_e32 v8, 16, v203
	v_and_b32_e32 v9, 0xffff0000, v203
	v_pk_fma_f32 v[8:9], v[56:57], v[2:3], v[8:9] op_sel_hi:[1,0,1]
	v_mov_b32_e32 v57, 0
	v_cvt_pk_bf16_f32 v7, v8, v9
	global_store_dwordx2 v[4:5], v[6:7], off offset:80
	v_mov_b32_e32 v56, 0
	v_mov_b32_e32 v54, 0
	s_waitcnt vmcnt(15)
	v_lshlrev_b32_e32 v8, 16, v204
	v_and_b32_e32 v9, 0xffff0000, v204
	v_pk_fma_f32 v[8:9], v[58:59], v[2:3], v[8:9] op_sel_hi:[1,0,1]
	v_mov_b32_e32 v59, 0
	v_cvt_pk_bf16_f32 v6, v8, v9
	v_lshlrev_b32_e32 v8, 16, v205
	v_and_b32_e32 v9, 0xffff0000, v205
	v_pk_fma_f32 v[8:9], v[60:61], v[2:3], v[8:9] op_sel_hi:[1,0,1]
	v_mov_b32_e32 v61, 0
	v_cvt_pk_bf16_f32 v7, v8, v9
	global_store_dwordx2 v[4:5], v[6:7], off offset:96
	v_mov_b32_e32 v60, 0
	v_mov_b32_e32 v58, 0
	s_waitcnt vmcnt(15)
	v_lshlrev_b32_e32 v8, 16, v206
	v_and_b32_e32 v9, 0xffff0000, v206
	v_pk_fma_f32 v[8:9], v[62:63], v[2:3], v[8:9] op_sel_hi:[1,0,1]
	v_mov_b32_e32 v63, 0
	v_cvt_pk_bf16_f32 v6, v8, v9
	v_lshlrev_b32_e32 v8, 16, v207
	v_and_b32_e32 v9, 0xffff0000, v207
	v_pk_fma_f32 v[8:9], v[64:65], v[2:3], v[8:9] op_sel_hi:[1,0,1]
	v_mov_b32_e32 v65, 0
	v_cvt_pk_bf16_f32 v7, v8, v9
	global_store_dwordx2 v[4:5], v[6:7], off offset:112
	v_mov_b32_e32 v64, 0
	v_mov_b32_e32 v62, 0
	s_waitcnt vmcnt(15)
	v_lshlrev_b32_e32 v8, 16, v208
	v_and_b32_e32 v9, 0xffff0000, v208
	v_pk_fma_f32 v[8:9], v[34:35], v[2:3], v[8:9] op_sel_hi:[1,0,1]
	v_mov_b32_e32 v35, 0
	v_cvt_pk_bf16_f32 v6, v8, v9
	v_lshlrev_b32_e32 v8, 16, v209
	v_and_b32_e32 v9, 0xffff0000, v209
	v_pk_fma_f32 v[8:9], v[36:37], v[2:3], v[8:9] op_sel_hi:[1,0,1]
	v_mov_b32_e32 v37, 0
	v_cvt_pk_bf16_f32 v7, v8, v9
	global_store_dwordx2 v[4:5], v[6:7], off offset:128
	v_mov_b32_e32 v36, 0
	v_mov_b32_e32 v34, 0
	s_waitcnt vmcnt(15)
	v_lshlrev_b32_e32 v8, 16, v210
	v_and_b32_e32 v9, 0xffff0000, v210
	v_pk_fma_f32 v[8:9], v[38:39], v[2:3], v[8:9] op_sel_hi:[1,0,1]
	v_mov_b32_e32 v39, 0
	v_cvt_pk_bf16_f32 v6, v8, v9
	v_lshlrev_b32_e32 v8, 16, v211
	v_and_b32_e32 v9, 0xffff0000, v211
	v_pk_fma_f32 v[8:9], v[40:41], v[2:3], v[8:9] op_sel_hi:[1,0,1]
	v_mov_b32_e32 v41, 0
	v_cvt_pk_bf16_f32 v7, v8, v9
	global_store_dwordx2 v[4:5], v[6:7], off offset:144
	v_mov_b32_e32 v40, 0
	v_mov_b32_e32 v38, 0
	s_waitcnt vmcnt(15)
	v_lshlrev_b32_e32 v8, 16, v212
	v_and_b32_e32 v9, 0xffff0000, v212
	v_pk_fma_f32 v[8:9], v[42:43], v[2:3], v[8:9] op_sel_hi:[1,0,1]
	v_mov_b32_e32 v43, 0
	v_cvt_pk_bf16_f32 v6, v8, v9
	v_lshlrev_b32_e32 v8, 16, v213
	v_and_b32_e32 v9, 0xffff0000, v213
	v_pk_fma_f32 v[8:9], v[44:45], v[2:3], v[8:9] op_sel_hi:[1,0,1]
	v_mov_b32_e32 v45, 0
	v_cvt_pk_bf16_f32 v7, v8, v9
	global_store_dwordx2 v[4:5], v[6:7], off offset:160
	v_mov_b32_e32 v44, 0
	v_mov_b32_e32 v42, 0
	s_waitcnt vmcnt(15)
	v_lshlrev_b32_e32 v8, 16, v214
	v_and_b32_e32 v9, 0xffff0000, v214
	v_pk_fma_f32 v[8:9], v[46:47], v[2:3], v[8:9] op_sel_hi:[1,0,1]
	v_mov_b32_e32 v47, 0
	v_cvt_pk_bf16_f32 v6, v8, v9
	v_lshlrev_b32_e32 v8, 16, v215
	v_and_b32_e32 v9, 0xffff0000, v215
	v_pk_fma_f32 v[8:9], v[48:49], v[2:3], v[8:9] op_sel_hi:[1,0,1]
	v_mov_b32_e32 v49, 0
	v_cvt_pk_bf16_f32 v7, v8, v9
	global_store_dwordx2 v[4:5], v[6:7], off offset:176
	v_mov_b32_e32 v48, 0
	v_mov_b32_e32 v46, 0
	s_waitcnt vmcnt(15)
	v_lshlrev_b32_e32 v8, 16, v216
	v_and_b32_e32 v9, 0xffff0000, v216
	v_pk_fma_f32 v[8:9], v[18:19], v[2:3], v[8:9] op_sel_hi:[1,0,1]
	v_mov_b32_e32 v19, 0
	v_cvt_pk_bf16_f32 v6, v8, v9
	v_lshlrev_b32_e32 v8, 16, v217
	v_and_b32_e32 v9, 0xffff0000, v217
	v_pk_fma_f32 v[8:9], v[20:21], v[2:3], v[8:9] op_sel_hi:[1,0,1]
	v_mov_b32_e32 v21, 0
	v_cvt_pk_bf16_f32 v7, v8, v9
	global_store_dwordx2 v[4:5], v[6:7], off offset:192
	v_mov_b32_e32 v20, 0
	v_mov_b32_e32 v18, 0
	s_waitcnt vmcnt(15)
	v_lshlrev_b32_e32 v8, 16, v218
	v_and_b32_e32 v9, 0xffff0000, v218
	v_pk_fma_f32 v[8:9], v[22:23], v[2:3], v[8:9] op_sel_hi:[1,0,1]
	v_mov_b32_e32 v23, 0
	v_cvt_pk_bf16_f32 v6, v8, v9
	v_lshlrev_b32_e32 v8, 16, v219
	v_and_b32_e32 v9, 0xffff0000, v219
	v_pk_fma_f32 v[8:9], v[24:25], v[2:3], v[8:9] op_sel_hi:[1,0,1]
	v_mov_b32_e32 v25, 0
	v_cvt_pk_bf16_f32 v7, v8, v9
	global_store_dwordx2 v[4:5], v[6:7], off offset:208
	v_mov_b32_e32 v24, 0
	v_mov_b32_e32 v22, 0
	s_waitcnt vmcnt(15)
	v_lshlrev_b32_e32 v8, 16, v220
	v_and_b32_e32 v9, 0xffff0000, v220
	v_pk_fma_f32 v[8:9], v[26:27], v[2:3], v[8:9] op_sel_hi:[1,0,1]
	v_mov_b32_e32 v27, 0
	v_cvt_pk_bf16_f32 v6, v8, v9
	v_lshlrev_b32_e32 v8, 16, v221
	v_and_b32_e32 v9, 0xffff0000, v221
	v_pk_fma_f32 v[8:9], v[28:29], v[2:3], v[8:9] op_sel_hi:[1,0,1]
	v_mov_b32_e32 v29, 0
	v_cvt_pk_bf16_f32 v7, v8, v9
	global_store_dwordx2 v[4:5], v[6:7], off offset:224
	v_mov_b32_e32 v28, 0
	v_mov_b32_e32 v26, 0
	s_waitcnt vmcnt(15)
	v_lshlrev_b32_e32 v8, 16, v222
	v_and_b32_e32 v9, 0xffff0000, v222
	v_pk_fma_f32 v[8:9], v[30:31], v[2:3], v[8:9] op_sel_hi:[1,0,1]
	v_mov_b32_e32 v31, 0
	v_cvt_pk_bf16_f32 v6, v8, v9
	v_lshlrev_b32_e32 v8, 16, v223
	v_and_b32_e32 v9, 0xffff0000, v223
	v_pk_fma_f32 v[8:9], v[32:33], v[2:3], v[8:9] op_sel_hi:[1,0,1]
	v_lshlrev_b32_e32 v2, 1, v168
	v_cvt_pk_bf16_f32 v7, v8, v9
	global_store_dwordx2 v[4:5], v[6:7], off offset:240
	v_lshl_add_u64 v[4:5], v[166:167], 1, s[6:7]
	v_lshl_add_u64 v[4:5], v[4:5], 0, v[2:3]
	s_barrier
	global_load_lds_dwordx4 v[4:5], off
	v_lshl_add_u64 v[4:5], s[4:5], 0, v[150:151]
	v_lshlrev_b32_e32 v2, 1, v156
	v_lshl_add_u64 v[4:5], v[4:5], 0, v[2:3]
	s_mov_b32 m0, s81
	v_lshlrev_b32_e32 v6, 1, v160
	global_load_lds_dwordx4 v[4:5], off
	v_lshl_add_u64 v[4:5], v[158:159], 1, s[6:7]
	v_mov_b32_e32 v7, v3
	v_lshl_add_u64 v[4:5], v[4:5], 0, v[6:7]
	s_mov_b32 m0, s82
	v_mov_b32_e32 v33, 0
	global_load_lds_dwordx4 v[4:5], off
	v_lshl_add_u64 v[4:5], s[4:5], 0, v[152:153]
	v_lshl_add_u64 v[4:5], v[4:5], 0, v[100:101]
	s_mov_b32 m0, s83
	v_mov_b32_e32 v32, 0
	global_load_lds_dwordx4 v[4:5], off
	v_mov_b32_e32 v30, 0
	v_mov_b32_e32 v9, 0
	v_mov_b32_e32 v8, 0
	v_mov_b32_e32 v7, 0
	v_mov_b32_e32 v6, 0
	v_mov_b32_e32 v5, 0
	v_mov_b32_e32 v4, 0
	s_cbranch_scc0 .LBB0_538
	s_bfe_u32 s1, s18, 0x20002
	s_and_b32 s4, s15, 3
	s_mul_i32 s1, s1, 0x3400000
	s_lshl_b32 s5, s4, 8
	s_add_i32 s4, s0, 64
	s_add_u32 s0, s1, s12
	s_addc_u32 s1, 0, s11
	s_add_u32 s0, s5, s0
	s_addc_u32 s1, 0, s1
	v_mov_b64_e32 v[4:5], s[0:1]
	s_movk_i32 s5, 0x6800
	v_and_b32_e32 v8, 15, v176
	v_mad_i64_i32 v[6:7], s[0:1], v154, s5, v[4:5]
	v_lshlrev_b32_e32 v8, 4, v8
	v_mov_b32_e32 v9, v3
	v_readlane_b32 s6, v247, 61
	v_lshl_add_u64 v[6:7], v[6:7], 0, v[8:9]
	v_readlane_b32 s7, v247, 62
	v_readlane_b32 s0, v246, 0
	v_mov_b32_e32 v18, v3
	v_lshl_add_u64 v[102:103], s[6:7], 0, v[6:7]
	v_add_u32_e32 v6, s0, v175
	v_mad_i64_i32 v[4:5], s[0:1], v6, s5, v[4:5]
	v_and_b32_e32 v6, 15, v177
	v_lshlrev_b32_e32 v6, 4, v6
	v_mov_b32_e32 v7, v3
	v_lshl_add_u64 v[4:5], v[4:5], 0, v[6:7]
	v_mov_b32_e32 v19, v3
	v_lshl_add_u64 v[104:105], s[6:7], 0, v[4:5]
	v_mov_b32_e32 v4, v3
	v_mov_b32_e32 v5, v3
	v_mov_b32_e32 v6, v3
	v_mov_b32_e32 v8, v3
	v_mov_b32_e32 v10, v3
	v_mov_b32_e32 v11, v3
	v_mov_b32_e32 v12, v3
	v_mov_b32_e32 v13, v3
	v_mov_b32_e32 v14, v3
	v_mov_b32_e32 v15, v3
	v_mov_b32_e32 v16, v3
	v_mov_b32_e32 v17, v3
	v_mov_b64_e32 v[34:35], v[18:19]
	v_mov_b64_e32 v[50:51], v[18:19]
	v_mov_b64_e32 v[66:67], v[18:19]
	v_add_u32_e32 v107, 0xfffffe01, v169
	s_mov_b32 s11, 0
	v_mov_b32_e32 v108, 0xff800000
	v_mov_b32_e32 v106, 0
	v_mov_b64_e32 v[32:33], v[16:17]
	v_mov_b64_e32 v[30:31], v[14:15]
	v_mov_b64_e32 v[28:29], v[12:13]
	v_mov_b64_e32 v[26:27], v[10:11]
	v_mov_b64_e32 v[24:25], v[8:9]
	v_mov_b64_e32 v[22:23], v[6:7]
	v_mov_b64_e32 v[20:21], v[4:5]
	v_mov_b64_e32 v[48:49], v[16:17]
	v_mov_b64_e32 v[46:47], v[14:15]
	v_mov_b64_e32 v[44:45], v[12:13]
	v_mov_b64_e32 v[42:43], v[10:11]
	v_mov_b64_e32 v[40:41], v[8:9]
	v_mov_b64_e32 v[38:39], v[6:7]
	v_mov_b64_e32 v[36:37], v[4:5]
	v_mov_b64_e32 v[64:65], v[16:17]
	v_mov_b64_e32 v[62:63], v[14:15]
	v_mov_b64_e32 v[60:61], v[12:13]
	v_mov_b64_e32 v[58:59], v[10:11]
	v_mov_b64_e32 v[56:57], v[8:9]
	v_mov_b64_e32 v[54:55], v[6:7]
	v_mov_b64_e32 v[52:53], v[4:5]
	s_branch .LBB0_612
